# cross-attention QK^T and SGU mixing loop: fragment LDS reads issued four steps ahead of their MFMAs (rotating buffers)
# baseline (speedup 1.0000x reference)
; #define LAS __attribute__((address_space(3)))
; __device__ __forceinline__ float fexp2(float x) { return __builtin_amdgcn_exp2f(x); }
; __device__ __forceinline__ f32x4 mfma16(bf16x8 a, bf16x8 b, f32x4 c) { return __builtin_amdgcn_mfma_f32_16x16x32_bf16(a, b, c, 0, 0, 0); }
; template <bool FOX> ...
;     f32x4 s[2][4];
; #pragma unroll
;     for (int mt = 0; mt < 4; ++mt) {
;         s[0][mt] = (f32x4){0.f, 0.f, 0.f, 0.f}; s[1][mt] = (f32x4){0.f, 0.f, 0.f, 0.f};
; #pragma unroll
;         for (int ks = 0; ks < 4; ++ks) { const bf16x8 kf = *(const LAS bf16x8*)(Ks + (mt * 16 + fr) * 136 + ks * 32 + fq * 8); s[0][mt] = mfma16(kf, qf[0][ks], s[0][mt]); s[1][mt] = mfma16(kf, qf[1][ks], s[1][mt]); }
;     }
;     if (FOX) {
; #pragma unroll
;         for (int mt = 0; mt < 4; ++mt) { const f32x4 ck = *(const LAS f32x4*)(cum + j * 64 + mt * 16 + fq * 4);
; #pragma unroll
;             for (int e = 0; e < 4; ++e) { s[0][mt][e] += cq[0] - ck[e]; s[1][mt][e] += cq[1] - ck[e]; } }
;         if (diag) {
; #pragma unroll
;             for (int g = 0; g < 2; ++g)
; #pragma unroll
;                 for (int mt = 0; mt < 4; ++mt)
; #pragma unroll
;                     for (int e = 0; e < 4; ++e) if (j * 64 + mt * 16 + fq * 4 + e > qpos[g]) s[g][mt][e] = -INFINITY;
;         }
;     }
;     bf16x8 pf[2][2];
; #pragma unroll
;     for (int g = 0; g < 2; ++g) {
;         float mx = -INFINITY;
; #pragma unroll
;         for (int mt = 0; mt < 4; ++mt)
; #pragma unroll
;             for (int e = 0; e < 4; ++e) mx = fmaxf(mx, s[g][mt][e]);
;         mx = fmaxf(mx, __shfl_xor(mx, 16)); mx = fmaxf(mx, __shfl_xor(mx, 32));
;         const float m_new = fmaxf(m_run[g], mx);
;         const float alpha = fexp2(m_run[g] - m_new);
;         float ls = 0.f;
; #pragma unroll
;         for (int mt = 0; mt < 4; ++mt)
; #pragma unroll
;             for (int e = 0; e < 4; ++e) { const float p = fexp2(s[g][mt][e] - m_new); s[g][mt][e] = p; ls += p; }
;         l_run[g] = l_run[g] * alpha + ls; m_run[g] = m_new;
; #pragma unroll
;         for (int i = 0; i < 8; ++i) o[g][i] *= alpha;
.LBB0_79:
	s_nop 1
	v_add_f32_e32 v112, 0, v196
	v_add_f32_e32 v112, v197, v112
	v_add_f32_e32 v112, v198, v112
	v_add_f32_e32 v112, v199, v112
	v_add_f32_e32 v112, v221, v112
	v_add_f32_e32 v112, v223, v112
	v_add_f32_e32 v112, v224, v112
	v_add_f32_e32 v113, v225, v112
	v_add_f32_e32 v112, 0, v222
	v_add_f32_e32 v112, v226, v112
	v_add_f32_e32 v112, v227, v112
	v_add_f32_e32 v112, v228, v112
	v_add_f32_e32 v112, v229, v112
	v_add_f32_e32 v112, v230, v112
	v_add_f32_e32 v112, v231, v112
	v_add_f32_e32 v112, v232, v112
	v_pk_add_f32 v[112:113], v[178:179], v[112:113]
	v_mov_b32_e32 v153, v160
	v_pk_add_f32 v[112:113], v[180:181], v[112:113]
	s_mov_b64 s[10:11], 0
	v_pk_add_f32 v[112:113], v[182:183], v[112:113]
	s_andn2_b64 vcc, exec, s[6:7]
	v_pk_add_f32 v[112:113], v[184:185], v[112:113]
	ds_read_b128 v[234:237], v220 offset:35840
	ds_read_b128 v[246:249], v220 offset:35904
	ds_read_b128 v[250:253], v220 offset:35968
	ds_read_b128 v[182:185], v220 offset:36032
	v_pk_add_f32 v[112:113], v[186:187], v[112:113]
	v_pk_add_f32 v[112:113], v[188:189], v[112:113]
	v_pk_add_f32 v[112:113], v[190:191], v[112:113]
	v_pk_add_f32 v[112:113], v[192:193], v[112:113]
	v_pk_fma_f32 v[176:177], v[176:177], v[152:153], v[112:113]
	s_waitcnt lgkmcnt(3)
	v_mfma_f32_16x16x32_bf16 v[132:135], v[234:237], v[0:3], 0
	v_mfma_f32_16x16x32_bf16 v[112:115], v[234:237], v[32:35], 0
	ds_read_b128 v[234:237], v220 offset:40192
	s_waitcnt lgkmcnt(3)
	v_mfma_f32_16x16x32_bf16 v[132:135], v[246:249], v[4:7], v[132:135]
	v_mfma_f32_16x16x32_bf16 v[112:115], v[246:249], v[36:39], v[112:115]
	ds_read_b128 v[246:249], v220 offset:40256
	s_waitcnt lgkmcnt(3)
	v_mfma_f32_16x16x32_bf16 v[132:135], v[250:253], v[8:11], v[132:135]
	v_mfma_f32_16x16x32_bf16 v[136:139], v[250:253], v[40:43], v[112:115]
	ds_read_b128 v[250:253], v220 offset:40320
	s_waitcnt lgkmcnt(3)
	v_mfma_f32_16x16x32_bf16 v[112:115], v[182:185], v[12:15], v[132:135]
	v_mfma_f32_16x16x32_bf16 v[132:135], v[182:185], v[44:47], v[136:139]
	ds_read_b128 v[182:185], v220 offset:40384
	s_nop 5
	s_waitcnt lgkmcnt(3)
	v_mfma_f32_16x16x32_bf16 v[140:143], v[234:237], v[0:3], 0
	v_max3_f32 v160, v112, s33, v113
	v_max3_f32 v160, v160, v114, v115
	v_mfma_f32_16x16x32_bf16 v[136:139], v[234:237], v[32:35], 0
	ds_read_b128 v[234:237], v220 offset:44544
	s_waitcnt lgkmcnt(3)
	v_mfma_f32_16x16x32_bf16 v[140:143], v[246:249], v[4:7], v[140:143]
	v_mfma_f32_16x16x32_bf16 v[136:139], v[246:249], v[36:39], v[136:139]
	ds_read_b128 v[246:249], v220 offset:44608
	s_waitcnt lgkmcnt(3)
	v_mfma_f32_16x16x32_bf16 v[140:143], v[250:253], v[8:11], v[140:143]
	v_mfma_f32_16x16x32_bf16 v[136:139], v[250:253], v[40:43], v[136:139]
	ds_read_b128 v[250:253], v220 offset:44672
	s_waitcnt lgkmcnt(3)
	v_mfma_f32_16x16x32_bf16 v[144:147], v[182:185], v[12:15], v[140:143]
	s_nop 5
	v_mfma_f32_16x16x32_bf16 v[136:139], v[182:185], v[44:47], v[136:139]
	ds_read_b128 v[182:185], v220 offset:44736
	v_max3_f32 v160, v160, v144, v145
	v_max3_f32 v160, v160, v146, v147
	s_waitcnt lgkmcnt(3)
	v_mfma_f32_16x16x32_bf16 v[148:151], v[234:237], v[0:3], 0
	v_mfma_f32_16x16x32_bf16 v[140:143], v[234:237], v[32:35], 0
	ds_read_b128 v[234:237], v220 offset:48896
	s_waitcnt lgkmcnt(3)
	v_mfma_f32_16x16x32_bf16 v[148:151], v[246:249], v[4:7], v[148:151]
	v_mfma_f32_16x16x32_bf16 v[140:143], v[246:249], v[36:39], v[140:143]
	ds_read_b128 v[246:249], v220 offset:48960
	s_waitcnt lgkmcnt(3)
	v_mfma_f32_16x16x32_bf16 v[148:151], v[250:253], v[8:11], v[148:151]
	v_mfma_f32_16x16x32_bf16 v[140:143], v[250:253], v[40:43], v[140:143]
	ds_read_b128 v[250:253], v220 offset:49024
	s_waitcnt lgkmcnt(3)
	v_mfma_f32_16x16x32_bf16 v[148:151], v[182:185], v[12:15], v[148:151]
	s_nop 7
	v_max3_f32 v160, v160, v148, v149
	v_mfma_f32_16x16x32_bf16 v[140:143], v[182:185], v[44:47], v[140:143]
	ds_read_b128 v[182:185], v220 offset:49088
	v_max3_f32 v160, v160, v150, v151
	s_waitcnt lgkmcnt(3)
	v_mfma_f32_16x16x32_bf16 v[178:181], v[234:237], v[0:3], 0
	v_mfma_f32_16x16x32_bf16 v[152:155], v[234:237], v[32:35], 0
	s_waitcnt lgkmcnt(2)
	v_mfma_f32_16x16x32_bf16 v[178:181], v[246:249], v[4:7], v[178:181]
	v_mfma_f32_16x16x32_bf16 v[152:155], v[246:249], v[36:39], v[152:155]
	s_waitcnt lgkmcnt(1)
	v_mfma_f32_16x16x32_bf16 v[178:181], v[250:253], v[8:11], v[178:181]
	v_mfma_f32_16x16x32_bf16 v[152:155], v[250:253], v[40:43], v[152:155]
	s_waitcnt lgkmcnt(0)
	v_mfma_f32_16x16x32_bf16 v[196:199], v[182:185], v[12:15], v[178:181]
	s_nop 7
	v_max3_f32 v160, v160, v196, v197
	v_max3_f32 v160, v160, v198, v199
	ds_bpermute_b32 v166, v201, v160
	v_mfma_f32_16x16x32_bf16 v[152:155], v[182:185], v[44:47], v[152:155]
	s_waitcnt lgkmcnt(0)
	v_max_f32_e32 v166, v166, v166
	v_max_f32_e32 v160, v160, v166
	ds_bpermute_b32 v166, v200, v160
	s_waitcnt lgkmcnt(0)
	v_max3_f32 v221, v195, v160, v166
	v_sub_f32_e32 v112, v112, v221
	v_exp_f32_e32 v112, v112
	v_sub_f32_e32 v113, v113, v221
	v_exp_f32_e32 v113, v113
	v_sub_f32_e32 v114, v114, v221
	v_exp_f32_e32 v114, v114
	v_sub_f32_e32 v115, v115, v221
	v_exp_f32_e32 v115, v115
	v_sub_f32_e32 v144, v144, v221
	v_add_f32_e32 v166, 0, v112
	v_exp_f32_e32 v167, v144
	v_add_f32_e32 v166, v113, v166
	v_add_f32_e32 v166, v114, v166
	v_add_f32_e32 v166, v115, v166
	v_sub_f32_e32 v145, v145, v221
	v_add_f32_e32 v144, v167, v166
	v_exp_f32_e32 v166, v145
	v_sub_f32_e32 v160, v195, v221
	v_exp_f32_e32 v160, v160
	v_cvt_pk_bf16_f32 v112, v112, v113
	v_add_f32_e32 v193, v166, v144
	v_sub_f32_e32 v144, v146, v221
	v_exp_f32_e32 v179, v144
	v_sub_f32_e32 v144, v147, v221
	v_exp_f32_e32 v181, v144
	v_sub_f32_e32 v144, v148, v221
	v_exp_f32_e32 v183, v144
	v_sub_f32_e32 v144, v149, v221
	v_pk_mul_f32 v[148:149], v[92:93], v[160:161] op_sel_hi:[1,0]
	v_pk_mul_f32 v[92:93], v[128:129], v[160:161] op_sel_hi:[1,0]
	v_max3_f32 v128, v132, s33, v133
	v_max3_f32 v128, v128, v134, v135
	v_max3_f32 v128, v128, v136, v137
	v_max3_f32 v128, v128, v138, v139
	v_max3_f32 v128, v128, v140, v141
	v_max3_f32 v128, v128, v142, v143
	v_max3_f32 v128, v128, v152, v153
	v_max3_f32 v128, v128, v154, v155
	ds_bpermute_b32 v129, v201, v128
	v_exp_f32_e32 v185, v144
	v_sub_f32_e32 v144, v150, v221
	v_exp_f32_e32 v187, v144
	v_sub_f32_e32 v144, v151, v221
	s_waitcnt lgkmcnt(0)
; __device__ __forceinline__ unsigned cvt_pk_bf16(float lo, float hi) { const f32x2_t v = {lo, hi}; const bf16x2_t b = __builtin_convertvector(v, bf16x2_t); return __builtin_bit_cast(unsigned, b); }
; __device__ __forceinline__ float fexp2(float x) { return __builtin_amdgcn_exp2f(x); }
; template <bool FOX> ...
;     ...
;     for (int g = 0; g < 2; ++g) {
;         float mx = -INFINITY;
; #pragma unroll
;         for (int mt = 0; mt < 4; ++mt)
; #pragma unroll
;             for (int e = 0; e < 4; ++e) mx = fmaxf(mx, s[g][mt][e]);
;         mx = fmaxf(mx, __shfl_xor(mx, 16)); mx = fmaxf(mx, __shfl_xor(mx, 32));
;         const float m_new = fmaxf(m_run[g], mx);
;         const float alpha = fexp2(m_run[g] - m_new);
;         float ls = 0.f;
; #pragma unroll
;         for (int mt = 0; mt < 4; ++mt)
; #pragma unroll
;             for (int e = 0; e < 4; ++e) { const float p = fexp2(s[g][mt][e] - m_new); s[g][mt][e] = p; ls += p; }
;         l_run[g] = l_run[g] * alpha + ls; m_run[g] = m_new;
; #pragma unroll
;         for (int i = 0; i < 8; ++i) o[g][i] *= alpha;
; #pragma unroll
;         for (int i = 0; i < 2; ++i) pf[g][i] = mk8(cvt_pk_bf16(s[g][2 * i][0], s[g][2 * i][1]), cvt_pk_bf16(s[g][2 * i][2], s[g][2 * i][3]), cvt_pk_bf16(s[g][2 * i + 1][0], s[g][2 * i + 1][1]), cvt_pk_bf16(s[g][2 * i + 1][2], s[g][2 * i + 1][3]));
;     }
	v_max_f32_e32 v129, v129, v129
	v_max_f32_e32 v128, v128, v129
	ds_bpermute_b32 v129, v200, v128
	v_pk_mul_f32 v[150:151], v[94:95], v[160:161] op_sel_hi:[1,0]
	v_pk_mul_f32 v[94:95], v[130:131], v[160:161] op_sel_hi:[1,0]
	v_cvt_pk_bf16_f32 v113, v114, v115
	v_cvt_pk_bf16_f32 v114, v167, v166
	s_waitcnt lgkmcnt(0)
	v_max3_f32 v222, v194, v128, v129
	v_sub_f32_e32 v129, v132, v222
	v_exp_f32_e32 v166, v129
	v_sub_f32_e32 v130, v133, v222
	v_exp_f32_e32 v167, v130
	v_sub_f32_e32 v130, v134, v222
	v_exp_f32_e32 v223, v130
	v_sub_f32_e32 v130, v135, v222
	v_exp_f32_e32 v224, v130
	v_sub_f32_e32 v130, v136, v222
	v_add_f32_e32 v129, 0, v166
	v_exp_f32_e32 v225, v130
	v_sub_f32_e32 v130, v137, v222
	v_add_f32_e32 v129, v167, v129
	v_exp_f32_e32 v226, v130
	v_add_f32_e32 v129, v223, v129
	v_add_f32_e32 v129, v224, v129
	v_add_f32_e32 v129, v225, v129
	v_add_f32_e32 v192, v226, v129
	v_sub_f32_e32 v129, v138, v222
	v_exp_f32_e32 v178, v129
	v_sub_f32_e32 v129, v139, v222
	v_exp_f32_e32 v180, v129
	v_sub_f32_e32 v129, v140, v222
	v_exp_f32_e32 v182, v129
	v_sub_f32_e32 v129, v141, v222
	v_exp_f32_e32 v184, v129
	v_sub_f32_e32 v129, v142, v222
	v_exp_f32_e32 v186, v129
	v_sub_f32_e32 v129, v143, v222
	v_sub_f32_e32 v128, v194, v222
	v_exp_f32_e32 v188, v129
	v_sub_f32_e32 v129, v152, v222
	v_exp_f32_e32 v190, v129
	v_sub_f32_e32 v129, v153, v222
	v_exp_f32_e32 v128, v128
	v_exp_f32_e32 v189, v144
	v_sub_f32_e32 v144, v196, v221
	v_exp_f32_e32 v194, v129
	v_sub_f32_e32 v129, v154, v222
	v_exp_f32_e32 v191, v144
	v_sub_f32_e32 v144, v197, v221
	v_exp_f32_e32 v196, v129
	v_sub_f32_e32 v129, v155, v222
	v_exp_f32_e32 v195, v144
	v_sub_f32_e32 v144, v198, v221
	v_exp_f32_e32 v198, v129
	v_mov_b32_e32 v129, v160
	v_pk_mul_f32 v[134:135], v[90:91], v[128:129] op_sel_hi:[1,0]
	v_pk_mul_f32 v[132:133], v[88:89], v[128:129] op_sel_hi:[1,0]
	ds_read2_b64 v[88:91], v211 offset1:4
	v_pk_add_f32 v[130:131], v[178:179], v[192:193]
	v_cvt_pk_bf16_f32 v115, v179, v181
	v_pk_add_f32 v[130:131], v[180:181], v[130:131]
	v_pk_mul_f32 v[138:139], v[98:99], v[128:129] op_sel_hi:[1,0]
	v_pk_add_f32 v[130:131], v[182:183], v[130:131]
	v_pk_mul_f32 v[136:137], v[96:97], v[128:129] op_sel_hi:[1,0]
	s_waitcnt lgkmcnt(0)
	v_mfma_f32_16x16x32_bf16 v[96:99], v[88:91], v[112:115], v[148:151]
	v_add_f32_e64 v130, v184, v130
	v_add_f32_e64 v131, v185, v131
	s_nop 0
	ds_read2_b64 v[148:151], v211 offset0:8 offset1:12
	v_exp_f32_e32 v197, v144
	v_sub_f32_e32 v144, v199, v221
	v_pk_add_f32 v[130:131], v[186:187], v[130:131]
	v_exp_f32_e32 v199, v144
	v_pk_add_f32 v[130:131], v[188:189], v[130:131]
	v_pk_mul_f32 v[66:67], v[66:67], v[128:129] op_sel_hi:[1,0]
	v_pk_add_f32 v[130:131], v[190:191], v[130:131]
	v_pk_mul_f32 v[64:65], v[64:65], v[128:129] op_sel_hi:[1,0]
	v_cvt_pk_bf16_f32 v140, v166, v167
	v_cvt_pk_bf16_f32 v141, v223, v224
	v_cvt_pk_bf16_f32 v142, v225, v226
	v_cvt_pk_bf16_f32 v143, v178, v180
	v_pk_add_f32 v[130:131], v[194:195], v[130:131]
	v_pk_mul_f32 v[146:147], v[102:103], v[160:161] op_sel_hi:[1,0]
	v_mfma_f32_16x16x32_bf16 v[64:67], v[88:91], v[140:143], v[64:67]
	v_add_f32_e64 v130, v196, v130
	v_add_f32_e64 v131, v197, v131
	v_pk_mul_f32 v[144:145], v[100:101], v[160:161] op_sel_hi:[1,0]
	v_pk_add_f32 v[130:131], v[198:199], v[130:131]
	v_cvt_pk_bf16_f32 v100, v183, v185
	v_cvt_pk_bf16_f32 v101, v187, v189
	v_cvt_pk_bf16_f32 v102, v191, v195
	v_cvt_pk_bf16_f32 v103, v197, v199
	v_pk_fma_f32 v[176:177], v[176:177], v[128:129], v[130:131]
	v_pk_mul_f32 v[70:71], v[70:71], v[128:129] op_sel_hi:[1,0]
	v_pk_mul_f32 v[68:69], v[68:69], v[128:129] op_sel_hi:[1,0]
	v_pk_mul_f32 v[74:75], v[74:75], v[128:129] op_sel_hi:[1,0]
	v_pk_mul_f32 v[72:73], v[72:73], v[128:129] op_sel_hi:[1,0]
	v_pk_mul_f32 v[78:79], v[78:79], v[128:129] op_sel_hi:[1,0]
	v_pk_mul_f32 v[76:77], v[76:77], v[128:129] op_sel_hi:[1,0]
	v_pk_mul_f32 v[82:83], v[82:83], v[128:129] op_sel_hi:[1,0]
	v_pk_mul_f32 v[80:81], v[80:81], v[128:129] op_sel_hi:[1,0]
	v_pk_mul_f32 v[86:87], v[86:87], v[128:129] op_sel_hi:[1,0]
	v_pk_mul_f32 v[84:85], v[84:85], v[128:129] op_sel_hi:[1,0]
	v_cvt_pk_bf16_f32 v128, v182, v184
	v_cvt_pk_bf16_f32 v129, v186, v188
	v_cvt_pk_bf16_f32 v130, v190, v194
	v_cvt_pk_bf16_f32 v131, v196, v198
	s_waitcnt lgkmcnt(0)
; #define LAS __attribute__((address_space(3)))
; __device__ __forceinline__ f32x4 mfma16(bf16x8 a, bf16x8 b, f32x4 c) { return __builtin_amdgcn_mfma_f32_16x16x32_bf16(a, b, c, 0, 0, 0); }
; template <bool FOX> ...
;     ...
; #pragma unroll
;     for (int dt = 0; dt < 8; ++dt)
; #pragma unroll
;         for (int i = 0; i < 2; ++i) {
;             const u32x2 lo = *(const LAS u32x2*)(Vt + (dt * 16 + fr) * 72 + i * 32 + fq * 4), hi2 = *(const LAS u32x2*)(Vt + (dt * 16 + fr) * 72 + i * 32 + 16 + fq * 4);
;             const bf16x8 vf = mk8(lo.x, lo.y, hi2.x, hi2.y);
;             o[0][dt] = mfma16(vf, pf[0][i], o[0][dt]); o[1][dt] = mfma16(vf, pf[1][i], o[1][dt]);
;         }
	v_mfma_f32_16x16x32_bf16 v[88:91], v[148:151], v[100:103], v[96:99]
	v_mul_f32_e64 v106, v106, v160
	v_mul_f32_e64 v107, v107, v160
	v_pk_mul_f32 v[104:105], v[104:105], v[160:161] op_sel_hi:[1,0]
	v_pk_mul_f32 v[118:119], v[118:119], v[160:161] op_sel_hi:[1,0]
	v_mfma_f32_16x16x32_bf16 v[64:67], v[148:151], v[128:131], v[64:67]
	v_add_u32_e32 v148, 0xd000, v208
	ds_read2_b64 v[96:99], v148 offset1:4
	ds_read2_b64 v[148:151], v148 offset0:8 offset1:12
	s_waitcnt lgkmcnt(1)
	v_mfma_f32_16x16x32_bf16 v[144:147], v[96:99], v[112:115], v[144:147]
	v_mul_f32_e64 v116, v116, v160
	v_mul_f32_e64 v117, v117, v160
	v_pk_mul_f32 v[122:123], v[122:123], v[160:161] op_sel_hi:[1,0]
	v_pk_mul_f32 v[120:121], v[120:121], v[160:161] op_sel_hi:[1,0]
	v_mfma_f32_16x16x32_bf16 v[68:71], v[96:99], v[140:143], v[68:71]
	v_mul_f32_e64 v126, v126, v160
	v_mul_f32_e64 v127, v127, v160
	v_pk_mul_f32 v[124:125], v[124:125], v[160:161] op_sel_hi:[1,0]
	v_pk_mul_f32 v[110:111], v[110:111], v[160:161] op_sel_hi:[1,0]
	s_waitcnt lgkmcnt(0)
	v_mfma_f32_16x16x32_bf16 v[96:99], v[148:151], v[100:103], v[144:147]
	v_mul_f32_e64 v108, v108, v160
	v_mul_f32_e64 v109, v109, v160
	v_mfma_f32_16x16x32_bf16 v[68:71], v[148:151], v[128:131], v[68:71]
	v_add_u32_e32 v148, 0xd000, v209
	ds_read2_b64 v[144:147], v148 offset1:4
	s_waitcnt lgkmcnt(0)
	v_mfma_f32_16x16x32_bf16 v[104:107], v[144:147], v[112:115], v[104:107]
	v_mfma_f32_16x16x32_bf16 v[72:75], v[144:147], v[140:143], v[72:75]
	ds_read2_b64 v[144:147], v148 offset0:8 offset1:12
	v_add_u32_e32 v148, 0xd000, v210
	s_waitcnt lgkmcnt(0)
	v_mfma_f32_16x16x32_bf16 v[104:107], v[144:147], v[100:103], v[104:107]
	v_mfma_f32_16x16x32_bf16 v[72:75], v[144:147], v[128:131], v[72:75]
	ds_read2_b64 v[144:147], v148 offset1:4
	s_waitcnt lgkmcnt(0)
	v_mfma_f32_16x16x32_bf16 v[116:119], v[144:147], v[112:115], v[116:119]
	v_mfma_f32_16x16x32_bf16 v[76:79], v[144:147], v[140:143], v[76:79]
	ds_read2_b64 v[144:147], v148 offset0:8 offset1:12
	v_add_u32_e32 v148, 0xf000, v207
	s_waitcnt lgkmcnt(0)
	v_mfma_f32_16x16x32_bf16 v[116:119], v[144:147], v[100:103], v[116:119]
	v_mfma_f32_16x16x32_bf16 v[76:79], v[144:147], v[128:131], v[76:79]
	ds_read2_b64 v[144:147], v148 offset0:128 offset1:132
	s_waitcnt lgkmcnt(0)
	v_mfma_f32_16x16x32_bf16 v[120:123], v[144:147], v[112:115], v[120:123]
	v_mfma_f32_16x16x32_bf16 v[80:83], v[144:147], v[140:143], v[80:83]
	ds_read2_b64 v[144:147], v148 offset0:136 offset1:140
	v_add_u32_e32 v148, 0xf800, v207
	s_waitcnt lgkmcnt(0)
	v_mfma_f32_16x16x32_bf16 v[120:123], v[144:147], v[100:103], v[120:123]
	v_mfma_f32_16x16x32_bf16 v[80:83], v[144:147], v[128:131], v[80:83]
	ds_read2_b64 v[144:147], v148 offset0:160 offset1:164
	s_waitcnt lgkmcnt(0)
	v_mfma_f32_16x16x32_bf16 v[124:127], v[144:147], v[112:115], v[124:127]
	v_mfma_f32_16x16x32_bf16 v[84:87], v[144:147], v[140:143], v[84:87]
	ds_read2_b64 v[144:147], v148 offset0:168 offset1:172
	v_add_u32_e32 v148, 0x3000, v211
	s_waitcnt lgkmcnt(0)
	v_mfma_f32_16x16x32_bf16 v[124:127], v[144:147], v[100:103], v[124:127]
	v_mfma_f32_16x16x32_bf16 v[84:87], v[144:147], v[128:131], v[84:87]
	ds_read2_b64 v[144:147], v148 offset0:192 offset1:196
	ds_read2_b64 v[148:151], v148 offset0:200 offset1:204
	s_waitcnt lgkmcnt(1)
	v_mfma_f32_16x16x32_bf16 v[92:95], v[144:147], v[112:115], v[92:95]
	v_mfma_f32_16x16x32_bf16 v[144:147], v[144:147], v[140:143], v[132:135]
	s_waitcnt lgkmcnt(0)
	v_mfma_f32_16x16x32_bf16 v[132:135], v[148:151], v[100:103], v[92:95]
	v_mfma_f32_16x16x32_bf16 v[92:95], v[148:151], v[128:131], v[144:147]
	v_add_u32_e32 v148, 0x3800, v211
	s_nop 3
	ds_read2_b64 v[144:147], v148 offset0:224 offset1:228
	s_waitcnt lgkmcnt(0)
	v_mfma_f32_16x16x32_bf16 v[108:111], v[144:147], v[112:115], v[108:111]
	v_mfma_f32_16x16x32_bf16 v[112:115], v[144:147], v[140:143], v[136:139]
	s_nop 2
	ds_read2_b64 v[136:139], v148 offset0:232 offset1:236
	s_waitcnt lgkmcnt(0)
	v_mfma_f32_16x16x32_bf16 v[108:111], v[136:139], v[100:103], v[108:111]
	s_barrier
	v_mfma_f32_16x16x32_bf16 v[100:103], v[136:139], v[128:131], v[112:115]
	s_cbranch_vccz .LBB0_77

; #define LAS __attribute__((address_space(3)))
; __device__ __forceinline__ float fexp2(float x) { return __builtin_amdgcn_exp2f(x); }
; __device__ __forceinline__ f32x4 mfma16(bf16x8 a, bf16x8 b, f32x4 c) { return __builtin_amdgcn_mfma_f32_16x16x32_bf16(a, b, c, 0, 0, 0); }
; template <bool FOX> ...
;     f32x4 s[2][4];
; #pragma unroll
;     for (int mt = 0; mt < 4; ++mt) {
;         s[0][mt] = (f32x4){0.f, 0.f, 0.f, 0.f}; s[1][mt] = (f32x4){0.f, 0.f, 0.f, 0.f};
; #pragma unroll
;         for (int ks = 0; ks < 4; ++ks) { const bf16x8 kf = *(const LAS bf16x8*)(Ks + (mt * 16 + fr) * 136 + ks * 32 + fq * 8); s[0][mt] = mfma16(kf, qf[0][ks], s[0][mt]); s[1][mt] = mfma16(kf, qf[1][ks], s[1][mt]); }
;     }
;     if (FOX) {
; #pragma unroll
;         for (int mt = 0; mt < 4; ++mt) { const f32x4 ck = *(const LAS f32x4*)(cum + j * 64 + mt * 16 + fq * 4);
; #pragma unroll
;             for (int e = 0; e < 4; ++e) { s[0][mt][e] += cq[0] - ck[e]; s[1][mt][e] += cq[1] - ck[e]; } }
;         if (diag) {
; #pragma unroll
;             for (int g = 0; g < 2; ++g)
; #pragma unroll
;                 for (int mt = 0; mt < 4; ++mt)
; #pragma unroll
;                     for (int e = 0; e < 4; ++e) if (j * 64 + mt * 16 + fq * 4 + e > qpos[g]) s[g][mt][e] = -INFINITY;
;         }
;     }
;     bf16x8 pf[2][2];
; #pragma unroll
;     for (int g = 0; g < 2; ++g) {
;         float mx = -INFINITY;
; #pragma unroll
;         for (int mt = 0; mt < 4; ++mt)
; #pragma unroll
;             for (int e = 0; e < 4; ++e) mx = fmaxf(mx, s[g][mt][e]);
;         mx = fmaxf(mx, __shfl_xor(mx, 16)); mx = fmaxf(mx, __shfl_xor(mx, 32));
;         const float m_new = fmaxf(m_run[g], mx);
;         const float alpha = fexp2(m_run[g] - m_new);
;         float ls = 0.f;
; #pragma unroll
;         for (int mt = 0; mt < 4; ++mt)
; #pragma unroll
;             for (int e = 0; e < 4; ++e) { const float p = fexp2(s[g][mt][e] - m_new); s[g][mt][e] = p; ls += p; }
;         l_run[g] = l_run[g] * alpha + ls; m_run[g] = m_new;
; #pragma unroll
;         for (int i = 0; i < 8; ++i) o[g][i] *= alpha;
.LBB0_82:
	ds_read_b128 v[234:237], v220
	ds_read_b128 v[246:249], v220 offset:64
	ds_read_b128 v[250:253], v220 offset:128
	ds_read_b128 v[178:181], v220 offset:192
	s_andn2_b64 vcc, exec, s[10:11]
	s_waitcnt lgkmcnt(3)
	v_mfma_f32_16x16x32_bf16 v[128:131], v[234:237], v[0:3], 0
	v_mfma_f32_16x16x32_bf16 v[112:115], v[234:237], v[32:35], 0
	ds_read_b128 v[234:237], v220 offset:4352
	s_waitcnt lgkmcnt(3)
	v_mfma_f32_16x16x32_bf16 v[128:131], v[246:249], v[4:7], v[128:131]
	v_mfma_f32_16x16x32_bf16 v[112:115], v[246:249], v[36:39], v[112:115]
	ds_read_b128 v[246:249], v220 offset:4416
	s_waitcnt lgkmcnt(3)
	v_mfma_f32_16x16x32_bf16 v[128:131], v[250:253], v[8:11], v[128:131]
	v_mfma_f32_16x16x32_bf16 v[136:139], v[250:253], v[40:43], v[112:115]
	ds_read_b128 v[250:253], v220 offset:4480
	s_waitcnt lgkmcnt(3)
	v_mfma_f32_16x16x32_bf16 v[112:115], v[178:181], v[12:15], v[128:131]
	v_mfma_f32_16x16x32_bf16 v[128:131], v[178:181], v[44:47], v[136:139]
	ds_read_b128 v[178:181], v220 offset:4544
	s_nop 5
	s_waitcnt lgkmcnt(3)
	v_mfma_f32_16x16x32_bf16 v[140:143], v[234:237], v[0:3], 0
	v_mfma_f32_16x16x32_bf16 v[136:139], v[234:237], v[32:35], 0
	ds_read_b128 v[234:237], v220 offset:8704
	s_waitcnt lgkmcnt(3)
	v_mfma_f32_16x16x32_bf16 v[140:143], v[246:249], v[4:7], v[140:143]
	v_mfma_f32_16x16x32_bf16 v[136:139], v[246:249], v[36:39], v[136:139]
	ds_read_b128 v[246:249], v220 offset:8768
	s_waitcnt lgkmcnt(3)
	v_mfma_f32_16x16x32_bf16 v[140:143], v[250:253], v[8:11], v[140:143]
	v_mfma_f32_16x16x32_bf16 v[136:139], v[250:253], v[40:43], v[136:139]
	ds_read_b128 v[250:253], v220 offset:8832
	s_waitcnt lgkmcnt(3)
	v_mfma_f32_16x16x32_bf16 v[148:151], v[178:181], v[12:15], v[140:143]
	v_mfma_f32_16x16x32_bf16 v[140:143], v[178:181], v[44:47], v[136:139]
	ds_read_b128 v[178:181], v220 offset:8896
	s_nop 3
	s_waitcnt lgkmcnt(3)
	v_mfma_f32_16x16x32_bf16 v[144:147], v[234:237], v[0:3], 0
	v_mfma_f32_16x16x32_bf16 v[136:139], v[234:237], v[32:35], 0
	ds_read_b128 v[234:237], v220 offset:13056
	s_waitcnt lgkmcnt(3)
	v_mfma_f32_16x16x32_bf16 v[144:147], v[246:249], v[4:7], v[144:147]
	v_mfma_f32_16x16x32_bf16 v[136:139], v[246:249], v[36:39], v[136:139]
	ds_read_b128 v[246:249], v220 offset:13120
	s_waitcnt lgkmcnt(3)
	v_mfma_f32_16x16x32_bf16 v[144:147], v[250:253], v[8:11], v[144:147]
	v_mfma_f32_16x16x32_bf16 v[136:139], v[250:253], v[40:43], v[136:139]
	ds_read_b128 v[250:253], v220 offset:13184
	s_waitcnt lgkmcnt(3)
	v_mfma_f32_16x16x32_bf16 v[182:185], v[178:181], v[12:15], v[144:147]
	v_mfma_f32_16x16x32_bf16 v[144:147], v[178:181], v[44:47], v[136:139]
	ds_read_b128 v[178:181], v220 offset:13248
	s_nop 3
	s_waitcnt lgkmcnt(3)
	v_mfma_f32_16x16x32_bf16 v[152:155], v[234:237], v[0:3], 0
	v_mfma_f32_16x16x32_bf16 v[136:139], v[234:237], v[32:35], 0
	s_waitcnt lgkmcnt(2)
	v_mfma_f32_16x16x32_bf16 v[152:155], v[246:249], v[4:7], v[152:155]
	v_mfma_f32_16x16x32_bf16 v[136:139], v[246:249], v[36:39], v[136:139]
	s_waitcnt lgkmcnt(1)
	v_mfma_f32_16x16x32_bf16 v[152:155], v[250:253], v[8:11], v[152:155]
	v_mfma_f32_16x16x32_bf16 v[136:139], v[250:253], v[40:43], v[136:139]
	s_waitcnt lgkmcnt(0)
	v_mfma_f32_16x16x32_bf16 v[190:193], v[178:181], v[12:15], v[152:155]
	v_mfma_f32_16x16x32_bf16 v[152:155], v[178:181], v[44:47], v[136:139]
	s_nop 3
	v_max3_f32 v136, v112, s33, v113
	v_max3_f32 v136, v136, v114, v115
	v_max3_f32 v136, v136, v148, v149
	v_max3_f32 v136, v136, v150, v151
	v_max3_f32 v136, v136, v182, v183
	v_max3_f32 v136, v136, v184, v185
	v_max3_f32 v136, v136, v190, v191
	v_max3_f32 v136, v136, v192, v193
	ds_bpermute_b32 v137, v201, v136
	s_waitcnt lgkmcnt(0)
	v_max_f32_e32 v137, v137, v137
	v_max_f32_e32 v136, v136, v137
	ds_bpermute_b32 v137, v200, v136
	s_waitcnt lgkmcnt(0)
	v_max3_f32 v195, v221, v136, v137
	v_sub_f32_e32 v136, v221, v195
	v_sub_f32_e32 v112, v112, v195
	v_exp_f32_e32 v196, v112
	v_sub_f32_e32 v112, v113, v195
	v_exp_f32_e32 v160, v136
	v_exp_f32_e32 v197, v112
	v_sub_f32_e32 v112, v114, v195
	v_exp_f32_e32 v198, v112
	v_sub_f32_e32 v112, v115, v195
	v_exp_f32_e32 v199, v112
	v_sub_f32_e32 v112, v148, v195
	v_exp_f32_e32 v221, v112
	v_sub_f32_e32 v112, v149, v195
	v_pk_mul_f32 v[148:149], v[88:89], v[160:161] op_sel_hi:[1,0]
	v_pk_mul_f32 v[88:89], v[132:133], v[160:161] op_sel_hi:[1,0]
	v_max3_f32 v132, v128, s33, v129
	v_max3_f32 v132, v132, v130, v131
	v_max3_f32 v132, v132, v140, v141
	v_max3_f32 v132, v132, v142, v143
	v_max3_f32 v132, v132, v144, v145
	v_max3_f32 v132, v132, v146, v147
	v_max3_f32 v132, v132, v152, v153
	v_max3_f32 v132, v132, v154, v155
	ds_bpermute_b32 v133, v201, v132
	v_exp_f32_e32 v223, v112
	v_sub_f32_e32 v112, v150, v195
	v_exp_f32_e32 v224, v112
	v_sub_f32_e32 v112, v151, v195
	s_waitcnt lgkmcnt(0)
	v_max_f32_e32 v133, v133, v133
	v_max_f32_e32 v132, v132, v133
	ds_bpermute_b32 v133, v200, v132
	v_exp_f32_e32 v225, v112
	v_sub_f32_e32 v112, v182, v195
	v_exp_f32_e32 v179, v112
	v_sub_f32_e32 v112, v183, v195
	s_waitcnt lgkmcnt(0)
; #define LAS __attribute__((address_space(3)))
; __device__ __forceinline__ unsigned cvt_pk_bf16(float lo, float hi) { const f32x2_t v = {lo, hi}; const bf16x2_t b = __builtin_convertvector(v, bf16x2_t); return __builtin_bit_cast(unsigned, b); }
; __device__ __forceinline__ float fexp2(float x) { return __builtin_amdgcn_exp2f(x); }
; __device__ __forceinline__ f32x4 mfma16(bf16x8 a, bf16x8 b, f32x4 c) { return __builtin_amdgcn_mfma_f32_16x16x32_bf16(a, b, c, 0, 0, 0); }
; template <bool FOX> ...
;     ...
;     for (int g = 0; g < 2; ++g) {
;         float mx = -INFINITY;
; #pragma unroll
;         for (int mt = 0; mt < 4; ++mt)
; #pragma unroll
;             for (int e = 0; e < 4; ++e) mx = fmaxf(mx, s[g][mt][e]);
;         mx = fmaxf(mx, __shfl_xor(mx, 16)); mx = fmaxf(mx, __shfl_xor(mx, 32));
;         const float m_new = fmaxf(m_run[g], mx);
;         const float alpha = fexp2(m_run[g] - m_new);
;         float ls = 0.f;
; #pragma unroll
;         for (int mt = 0; mt < 4; ++mt)
; #pragma unroll
;             for (int e = 0; e < 4; ++e) { const float p = fexp2(s[g][mt][e] - m_new); s[g][mt][e] = p; ls += p; }
;         l_run[g] = l_run[g] * alpha + ls; m_run[g] = m_new;
; #pragma unroll
;         for (int i = 0; i < 8; ++i) o[g][i] *= alpha;
; #pragma unroll
;         for (int i = 0; i < 2; ++i) pf[g][i] = mk8(cvt_pk_bf16(s[g][2 * i][0], s[g][2 * i][1]), cvt_pk_bf16(s[g][2 * i][2], s[g][2 * i][3]), cvt_pk_bf16(s[g][2 * i + 1][0], s[g][2 * i + 1][1]), cvt_pk_bf16(s[g][2 * i + 1][2], s[g][2 * i + 1][3]));
;     }
; #pragma unroll
;     for (int dt = 0; dt < 8; ++dt)
; #pragma unroll
;         for (int i = 0; i < 2; ++i) {
;             const u32x2 lo = *(const LAS u32x2*)(Vt + (dt * 16 + fr) * 72 + i * 32 + fq * 4), hi2 = *(const LAS u32x2*)(Vt + (dt * 16 + fr) * 72 + i * 32 + 16 + fq * 4);
;             const bf16x8 vf = mk8(lo.x, lo.y, hi2.x, hi2.y);
;             o[0][dt] = mfma16(vf, pf[0][i], o[0][dt]); o[1][dt] = mfma16(vf, pf[1][i], o[1][dt]);
	v_max3_f32 v194, v222, v132, v133
	v_sub_f32_e32 v128, v128, v194
	v_sub_f32_e32 v132, v222, v194
	v_exp_f32_e32 v222, v128
	v_sub_f32_e32 v128, v129, v194
	v_exp_f32_e32 v226, v128
	v_sub_f32_e32 v128, v130, v194
	v_exp_f32_e32 v227, v128
	v_sub_f32_e32 v128, v131, v194
	v_exp_f32_e32 v228, v128
	v_sub_f32_e32 v128, v140, v194
	v_exp_f32_e32 v229, v128
	v_sub_f32_e32 v128, v141, v194
	v_exp_f32_e32 v230, v128
	v_sub_f32_e32 v128, v142, v194
	v_exp_f32_e32 v231, v128
	v_sub_f32_e32 v128, v143, v194
	v_exp_f32_e32 v232, v128
	v_sub_f32_e32 v128, v144, v194
	v_exp_f32_e32 v178, v128
	v_sub_f32_e32 v128, v145, v194
	v_exp_f32_e32 v180, v128
	v_sub_f32_e32 v128, v146, v194
	v_exp_f32_e32 v182, v128
	v_sub_f32_e32 v128, v147, v194
	v_exp_f32_e32 v181, v112
	v_sub_f32_e32 v112, v184, v195
	v_exp_f32_e32 v184, v128
	v_sub_f32_e32 v128, v152, v194
	v_exp_f32_e32 v152, v132
	v_exp_f32_e32 v183, v112
	v_sub_f32_e32 v112, v185, v195
	v_exp_f32_e32 v186, v128
	v_sub_f32_e32 v128, v153, v194
	v_exp_f32_e32 v185, v112
	v_sub_f32_e32 v112, v190, v195
	v_exp_f32_e32 v188, v128
	v_sub_f32_e32 v128, v154, v194
	v_exp_f32_e32 v187, v112
	v_sub_f32_e32 v112, v191, v195
	v_exp_f32_e32 v190, v128
	v_sub_f32_e32 v128, v155, v194
	v_exp_f32_e32 v189, v112
	v_sub_f32_e32 v112, v192, v195
	v_pk_mul_f32 v[150:151], v[90:91], v[160:161] op_sel_hi:[1,0]
	v_pk_mul_f32 v[90:91], v[134:135], v[160:161] op_sel_hi:[1,0]
	v_exp_f32_e32 v192, v128
	v_pk_mul_f32 v[66:67], v[66:67], v[152:153] op_sel_hi:[1,0]
	v_pk_mul_f32 v[64:65], v[64:65], v[152:153] op_sel_hi:[1,0]
	v_pk_mul_f32 v[70:71], v[70:71], v[152:153] op_sel_hi:[1,0]
	v_pk_mul_f32 v[68:69], v[68:69], v[152:153] op_sel_hi:[1,0]
	v_pk_mul_f32 v[74:75], v[74:75], v[152:153] op_sel_hi:[1,0]
	v_pk_mul_f32 v[72:73], v[72:73], v[152:153] op_sel_hi:[1,0]
	v_pk_mul_f32 v[78:79], v[78:79], v[152:153] op_sel_hi:[1,0]
	v_pk_mul_f32 v[76:77], v[76:77], v[152:153] op_sel_hi:[1,0]
	v_pk_mul_f32 v[82:83], v[82:83], v[152:153] op_sel_hi:[1,0]
	v_pk_mul_f32 v[80:81], v[80:81], v[152:153] op_sel_hi:[1,0]
	v_pk_mul_f32 v[86:87], v[86:87], v[152:153] op_sel_hi:[1,0]
	v_pk_mul_f32 v[84:85], v[84:85], v[152:153] op_sel_hi:[1,0]
	v_pk_mul_f32 v[130:131], v[94:95], v[152:153] op_sel_hi:[1,0]
	v_pk_mul_f32 v[128:129], v[92:93], v[152:153] op_sel_hi:[1,0]
	v_pk_mul_f32 v[134:135], v[102:103], v[152:153] op_sel_hi:[1,0]
	v_pk_mul_f32 v[132:133], v[100:101], v[152:153] op_sel_hi:[1,0]
	v_add_u32_e32 v153, 0x4000, v207
	ds_read2_b64 v[92:95], v153 offset0:128 offset1:132
	v_exp_f32_e32 v191, v112
	v_sub_f32_e32 v112, v193, v195
	v_exp_f32_e32 v193, v112
	v_cvt_pk_bf16_f32 v112, v196, v197
	v_cvt_pk_bf16_f32 v113, v198, v199
	v_cvt_pk_bf16_f32 v114, v221, v223
	v_cvt_pk_bf16_f32 v115, v224, v225
	v_cvt_pk_bf16_f32 v140, v222, v226
	v_cvt_pk_bf16_f32 v141, v227, v228
	s_waitcnt lgkmcnt(0)
	v_mfma_f32_16x16x32_bf16 v[100:103], v[92:95], v[112:115], v[148:151]
	v_cvt_pk_bf16_f32 v142, v229, v230
	v_cvt_pk_bf16_f32 v143, v231, v232
	v_pk_mul_f32 v[138:139], v[98:99], v[160:161] op_sel_hi:[1,0]
	ds_read2_b64 v[148:151], v153 offset0:136 offset1:140
	v_mfma_f32_16x16x32_bf16 v[64:67], v[92:95], v[140:143], v[64:67]
	v_mul_f32_e64 v136, v96, v160
	v_mul_f32_e64 v137, v97, v160
	v_cvt_pk_bf16_f32 v96, v179, v181
	v_cvt_pk_bf16_f32 v97, v183, v185
	v_cvt_pk_bf16_f32 v98, v187, v189
	v_cvt_pk_bf16_f32 v99, v191, v193
	v_cvt_pk_bf16_f32 v144, v178, v180
	v_cvt_pk_bf16_f32 v145, v182, v184
	v_cvt_pk_bf16_f32 v146, v186, v188
	v_cvt_pk_bf16_f32 v147, v190, v192
	s_waitcnt lgkmcnt(0)
	v_mfma_f32_16x16x32_bf16 v[92:95], v[148:151], v[96:99], v[100:103]
	v_mul_f32_e64 v106, v106, v160
	v_mul_f32_e64 v107, v107, v160
	v_pk_mul_f32 v[104:105], v[104:105], v[160:161] op_sel_hi:[1,0]
	v_pk_mul_f32 v[118:119], v[118:119], v[160:161] op_sel_hi:[1,0]
	v_mfma_f32_16x16x32_bf16 v[64:67], v[148:151], v[144:147], v[64:67]
	v_add_u32_e32 v148, 0x4000, v208
	ds_read2_b64 v[100:103], v148 offset0:128 offset1:132
	ds_read2_b64 v[148:151], v148 offset0:136 offset1:140
	s_waitcnt lgkmcnt(1)
; #define LAS __attribute__((address_space(3)))
; __device__ __forceinline__ f32x4 mfma16(bf16x8 a, bf16x8 b, f32x4 c) { return __builtin_amdgcn_mfma_f32_16x16x32_bf16(a, b, c, 0, 0, 0); }
; template <bool FOX> ...
;     ...
; #pragma unroll
;     for (int dt = 0; dt < 8; ++dt)
; #pragma unroll
;         for (int i = 0; i < 2; ++i) {
;             const u32x2 lo = *(const LAS u32x2*)(Vt + (dt * 16 + fr) * 72 + i * 32 + fq * 4), hi2 = *(const LAS u32x2*)(Vt + (dt * 16 + fr) * 72 + i * 32 + 16 + fq * 4);
;             const bf16x8 vf = mk8(lo.x, lo.y, hi2.x, hi2.y);
;             o[0][dt] = mfma16(vf, pf[0][i], o[0][dt]); o[1][dt] = mfma16(vf, pf[1][i], o[1][dt]);
;         }
	v_mfma_f32_16x16x32_bf16 v[136:139], v[100:103], v[112:115], v[136:139]
	v_mul_f32_e64 v116, v116, v160
	v_mul_f32_e64 v117, v117, v160
	v_pk_mul_f32 v[122:123], v[122:123], v[160:161] op_sel_hi:[1,0]
	v_pk_mul_f32 v[120:121], v[120:121], v[160:161] op_sel_hi:[1,0]
	v_mfma_f32_16x16x32_bf16 v[68:71], v[100:103], v[140:143], v[68:71]
	v_mul_f32_e64 v126, v126, v160
	v_mul_f32_e64 v127, v127, v160
	v_pk_mul_f32 v[124:125], v[124:125], v[160:161] op_sel_hi:[1,0]
	v_pk_mul_f32 v[110:111], v[110:111], v[160:161] op_sel_hi:[1,0]
	s_waitcnt lgkmcnt(0)
	v_mfma_f32_16x16x32_bf16 v[100:103], v[148:151], v[96:99], v[136:139]
	v_mul_f32_e64 v108, v108, v160
	v_mul_f32_e64 v109, v109, v160
	v_mfma_f32_16x16x32_bf16 v[68:71], v[148:151], v[144:147], v[68:71]
	v_add_u32_e32 v148, 0x4000, v209
	ds_read2_b64 v[136:139], v148 offset0:128 offset1:132
	s_waitcnt lgkmcnt(0)
	v_mfma_f32_16x16x32_bf16 v[104:107], v[136:139], v[112:115], v[104:107]
	v_mfma_f32_16x16x32_bf16 v[72:75], v[136:139], v[140:143], v[72:75]
	ds_read2_b64 v[136:139], v148 offset0:136 offset1:140
	v_add_u32_e32 v148, 0x4000, v210
	s_waitcnt lgkmcnt(0)
	v_mfma_f32_16x16x32_bf16 v[104:107], v[136:139], v[96:99], v[104:107]
	v_mfma_f32_16x16x32_bf16 v[72:75], v[136:139], v[144:147], v[72:75]
	ds_read2_b64 v[136:139], v148 offset0:128 offset1:132
	s_waitcnt lgkmcnt(0)
	v_mfma_f32_16x16x32_bf16 v[116:119], v[136:139], v[112:115], v[116:119]
	v_mfma_f32_16x16x32_bf16 v[76:79], v[136:139], v[140:143], v[76:79]
	ds_read2_b64 v[136:139], v148 offset0:136 offset1:140
	v_add_u32_e32 v148, 0x6800, v207
	s_waitcnt lgkmcnt(0)
	v_mfma_f32_16x16x32_bf16 v[116:119], v[136:139], v[96:99], v[116:119]
	v_mfma_f32_16x16x32_bf16 v[76:79], v[136:139], v[144:147], v[76:79]
	ds_read2_b64 v[136:139], v148 offset1:4
	s_waitcnt lgkmcnt(0)
	v_mfma_f32_16x16x32_bf16 v[120:123], v[136:139], v[112:115], v[120:123]
	v_mfma_f32_16x16x32_bf16 v[80:83], v[136:139], v[140:143], v[80:83]
	ds_read2_b64 v[136:139], v148 offset0:8 offset1:12
	v_add_u32_e32 v148, 0x7000, v207
	s_waitcnt lgkmcnt(0)
	v_mfma_f32_16x16x32_bf16 v[120:123], v[136:139], v[96:99], v[120:123]
	v_mfma_f32_16x16x32_bf16 v[80:83], v[136:139], v[144:147], v[80:83]
	ds_read2_b64 v[136:139], v148 offset0:32 offset1:36
	s_waitcnt lgkmcnt(0)
	v_mfma_f32_16x16x32_bf16 v[124:127], v[136:139], v[112:115], v[124:127]
	v_mfma_f32_16x16x32_bf16 v[84:87], v[136:139], v[140:143], v[84:87]
	ds_read2_b64 v[136:139], v148 offset0:40 offset1:44
	v_add_u32_e32 v148, 0x7800, v207
	s_waitcnt lgkmcnt(0)
	v_mfma_f32_16x16x32_bf16 v[124:127], v[136:139], v[96:99], v[124:127]
	v_mfma_f32_16x16x32_bf16 v[84:87], v[136:139], v[144:147], v[84:87]
	ds_read2_b64 v[136:139], v148 offset0:64 offset1:68
	ds_read2_b64 v[148:151], v148 offset0:72 offset1:76
	s_waitcnt lgkmcnt(1)
	v_mfma_f32_16x16x32_bf16 v[88:91], v[136:139], v[112:115], v[88:91]
	v_mfma_f32_16x16x32_bf16 v[136:139], v[136:139], v[140:143], v[128:131]
	s_waitcnt lgkmcnt(0)
	v_mfma_f32_16x16x32_bf16 v[128:131], v[148:151], v[96:99], v[88:91]
	v_mfma_f32_16x16x32_bf16 v[88:91], v[148:151], v[144:147], v[136:139]
	v_add_u32_e32 v148, 0x8000, v207
	s_nop 3
	ds_read2_b64 v[136:139], v148 offset0:96 offset1:100
	s_waitcnt lgkmcnt(0)
	v_mfma_f32_16x16x32_bf16 v[108:111], v[136:139], v[112:115], v[108:111]
	v_mfma_f32_16x16x32_bf16 v[112:115], v[136:139], v[140:143], v[132:135]
	s_nop 2
	ds_read2_b64 v[132:135], v148 offset0:104 offset1:108
	s_waitcnt lgkmcnt(0)
	v_mfma_f32_16x16x32_bf16 v[108:111], v[132:135], v[96:99], v[108:111]
	s_barrier
	v_mfma_f32_16x16x32_bf16 v[96:99], v[132:135], v[144:147], v[112:115]
	s_cbranch_vccnz .LBB0_79
	ds_write_b128 v202, v[24:27]
	ds_write_b16 v203, v20 offset:17408
	ds_write_b16 v203, v212 offset:17552
	ds_write_b16 v203, v21 offset:17696
	ds_write_b16 v203, v213 offset:17840
	ds_write_b16 v203, v22 offset:17984
	ds_write_b16 v203, v214 offset:18128
	ds_write_b16 v203, v23 offset:18272
	ds_write_b16 v203, v215 offset:18416
	ds_write_b128 v204, v[16:19]
	ds_write_b16 v205, v28 offset:17408
	ds_write_b16 v205, v216 offset:17552
	ds_write_b16 v205, v29 offset:17696
	ds_write_b16 v205, v217 offset:17840
	ds_write_b16 v205, v30 offset:17984
	ds_write_b16 v205, v218 offset:18128
	ds_write_b16 v205, v31 offset:18272
	ds_write_b16 v205, v219 offset:18416
	s_branch .LBB0_79

; #define LAS __attribute__((address_space(3)))
; __device__ __forceinline__ unsigned cvt_pk_bf16(float lo, float hi) { const f32x2_t v = {lo, hi}; const bf16x2_t b = __builtin_convertvector(v, bf16x2_t); return __builtin_bit_cast(unsigned, b); }
; __device__ __forceinline__ f32x4 mfma16(bf16x8 a, bf16x8 b, f32x4 c) { return __builtin_amdgcn_mfma_f32_16x16x32_bf16(a, b, c, 0, 0, 0); }
; __device__ __forceinline__ void sgu_unit(LAS unsigned char* lds, int b, int n, int g, const bf16_t* V, bf16_t* U, const float* ln_g, const float* ln_b, const float* w_s, const float* b_s, bool dry) {
;     ...
;     for (int ks = 0; ks < nks; ++ks) {
;         const float* wp = w_s + ((size_t)g * 128 + t) * 128 + ks * 32 + fq * 8;
;         f32x4 w0 = *(const f32x4*)wp, w1 = *(const f32x4*)(wp + 4);
;         const int sb = ks * 32 + fq * 8;
; #pragma unroll
;         for (int e = 0; e < 4; ++e) { if (sb + e > t) w0[e] = 0.f; if (sb + 4 + e > t) w1[e] = 0.f; }
;         const bf16x8 wf = mk8(cvt_pk_bf16(w0[0], w0[1]), cvt_pk_bf16(w0[2], w0[3]), cvt_pk_bf16(w1[0], w1[1]), cvt_pk_bf16(w1[2], w1[3]));
; #pragma unroll
;         for (int nt = 0; nt < 16; ++nt) { const bf16x8 vf = *(const LAS bf16x8*)(vt + (nt * 16 + fr) * 136 + ks * 32 + fq * 8); acc[nt] = mfma16(vf, wf, acc[nt]); }
;     }
.LBB0_315:
	v_lshl_add_u64 v[74:75], s[28:29], 2, v[70:71]
	global_load_dwordx4 v[64:67], v[74:75], off offset:16
	s_nop 0
	global_load_dwordx4 v[74:77], v[74:75], off
	v_add_u32_e32 v73, s28, v160
	v_cmp_gt_i32_e32 vcc, v73, v68
	v_mov_b32_e32 v78, s29
	v_add_u32_e32 v72, -1, v72
	s_add_i32 s28, s28, 32
	s_waitcnt vmcnt(0)
	v_cndmask_b32_e32 v81, v74, v78, vcc
	v_add_u32_e32 v78, 4, v73
	v_cndmask_b32_e32 v79, v76, v76, vcc
	v_cndmask_b32_e32 v80, v77, v77, vcc
	v_cmp_gt_i32_e32 vcc, v78, v68
	v_mov_b32_e32 v78, s29
	s_nop 0
	v_cndmask_b32_e32 v78, v64, v78, vcc
	v_cndmask_b32_e32 v64, v67, v67, vcc
	v_cndmask_b32_e32 v66, v66, v66, vcc
	v_cndmask_b32_e32 v65, v65, v65, vcc
	v_cmp_lt_i32_e32 vcc, v73, v68
	s_nop 1
	v_cndmask_b32_e32 v67, v81, v74, vcc
	v_cndmask_b32_e32 v74, v80, v77, vcc
	v_add_u32_e32 v77, 5, v73
	v_cndmask_b32_e32 v76, v79, v76, vcc
	v_cndmask_b32_e32 v75, 0, v75, vcc
	v_cmp_le_i32_e32 vcc, v77, v68
	s_nop 1
	v_cndmask_b32_e32 v77, 0, v65, vcc
	v_add_u32_e32 v65, 2, v73
	v_cmp_le_i32_e32 vcc, v65, v68
	s_nop 1
	v_cndmask_b32_e32 v65, 0, v76, vcc
	v_add_u32_e32 v76, 6, v73
	v_cmp_le_i32_e32 vcc, v76, v68
	s_nop 1
	v_cndmask_b32_e32 v76, 0, v66, vcc
	v_add_u32_e32 v66, 3, v73
	v_cmp_le_i32_e32 vcc, v66, v68
	v_add_u32_e32 v73, 7, v73
	s_nop 0
	v_cndmask_b32_e32 v66, 0, v74, vcc
	v_cmp_le_i32_e32 vcc, v73, v68
	v_cvt_pk_bf16_f32 v65, v65, v66
	v_cvt_pk_bf16_f32 v66, v78, v77
	v_cndmask_b32_e32 v73, 0, v64, vcc
	v_cvt_pk_bf16_f32 v64, v67, v75
	v_cvt_pk_bf16_f32 v67, v76, v73
	ds_read_b128 v[74:77], v69
	ds_read_b128 v[82:85], v69 offset:4352
	ds_read_b128 v[86:89], v69 offset:8704
	ds_read_b128 v[90:93], v69 offset:13056
	v_cmp_eq_u32_e32 vcc, 0, v72
	s_waitcnt lgkmcnt(3)
	v_mfma_f32_16x16x32_bf16 v[60:63], v[74:77], v[64:67], v[60:63]
	ds_read_b128 v[74:77], v69 offset:17408
	s_or_b64 s[12:13], vcc, s[12:13]
	s_waitcnt lgkmcnt(3)
	v_mfma_f32_16x16x32_bf16 v[56:59], v[82:85], v[64:67], v[56:59]
	ds_read_b128 v[82:85], v69 offset:21760
	s_waitcnt lgkmcnt(3)
	v_mfma_f32_16x16x32_bf16 v[52:55], v[86:89], v[64:67], v[52:55]
	ds_read_b128 v[86:89], v69 offset:26112
	s_waitcnt lgkmcnt(3)
	v_mfma_f32_16x16x32_bf16 v[48:51], v[90:93], v[64:67], v[48:51]
	ds_read_b128 v[90:93], v69 offset:30464
	s_waitcnt lgkmcnt(3)
	v_mfma_f32_16x16x32_bf16 v[44:47], v[74:77], v[64:67], v[44:47]
	ds_read_b128 v[74:77], v69 offset:34816
	s_waitcnt lgkmcnt(3)
	v_mfma_f32_16x16x32_bf16 v[40:43], v[82:85], v[64:67], v[40:43]
	ds_read_b128 v[82:85], v69 offset:39168
	s_waitcnt lgkmcnt(3)
	v_mfma_f32_16x16x32_bf16 v[36:39], v[86:89], v[64:67], v[36:39]
	ds_read_b128 v[86:89], v69 offset:43520
	s_waitcnt lgkmcnt(3)
	v_mfma_f32_16x16x32_bf16 v[32:35], v[90:93], v[64:67], v[32:35]
	ds_read_b128 v[90:93], v69 offset:47872
	s_waitcnt lgkmcnt(3)
	v_mfma_f32_16x16x32_bf16 v[28:31], v[74:77], v[64:67], v[28:31]
	ds_read_b128 v[74:77], v69 offset:52224
	s_waitcnt lgkmcnt(3)
	v_mfma_f32_16x16x32_bf16 v[24:27], v[82:85], v[64:67], v[24:27]
	ds_read_b128 v[82:85], v69 offset:56576
	s_waitcnt lgkmcnt(3)
	v_mfma_f32_16x16x32_bf16 v[20:23], v[86:89], v[64:67], v[20:23]
	ds_read_b128 v[86:89], v69 offset:60928
	s_waitcnt lgkmcnt(3)
	v_mfma_f32_16x16x32_bf16 v[16:19], v[90:93], v[64:67], v[16:19]
	ds_read_b128 v[90:93], v69 offset:65280
	s_waitcnt lgkmcnt(3)
	v_mfma_f32_16x16x32_bf16 v[12:15], v[74:77], v[64:67], v[12:15]
	s_waitcnt lgkmcnt(2)
	v_mfma_f32_16x16x32_bf16 v[8:11], v[82:85], v[64:67], v[8:11]
	s_waitcnt lgkmcnt(1)
	v_mfma_f32_16x16x32_bf16 v[4:7], v[86:89], v[64:67], v[4:7]
	v_add_u32_e32 v69, 64, v69
	s_waitcnt lgkmcnt(0)
	v_mfma_f32_16x16x32_bf16 v[0:3], v[90:93], v[64:67], v[0:3]
	s_andn2_b64 exec, exec, s[12:13]
	s_cbranch_execnz .LBB0_315
	s_or_b64 exec, exec, s[12:13]
